# attention key loop: K-tile DMA issue also moved behind the hoisted fragment reads and first QK chain
# baseline (speedup 1.0000x reference)
; DI void attn_item(const Params& p, int l, bool isS, int b, int h, int cp, char* smem) {
;     ...
;   asm volatile("s_waitcnt lgkmcnt(0)" ::: "memory");
;   __builtin_amdgcn_s_barrier();
;   for (int j = 0; j < nkt; ++j) {
;     if (j + 2 < nkt) issue_k(j + 2);
;     if (j + 1 < nkt) issue_v(j + 1);
;     const bool doPV = wactive && j < mykt;
;     const bool doQK = wactive && j + 1 < mykt;
;     f32x4 st[2][4];
;     bf16x8 pfn[2][2];
;     float alpha[2] = {1.f, 1.f}, psum[2] = {0.f, 0.f}; bool moved[2] = {false, false};
.LBB0_1366:
	s_or_b64 exec, exec, s[30:31]
	s_waitcnt lgkmcnt(0)
	s_cmp_lt_i32 s9, 1
	s_barrier
	s_cbranch_scc1 .LBB0_1387
	s_or_b32 s11, s11, 1
	v_mov_b32_e32 v2, s20
	v_mov_b32_e32 v20, s11
	v_cmp_gt_i32_e32 vcc, 4, v57
	v_bfe_u32 v21, v54, 1, 3
	v_mov_b32_e32 v53, v173
	v_cndmask_b32_e32 v2, v2, v20, vcc
	v_lshrrev_b32_e32 v20, 1, v54
	v_bitop3_b32 v20, v56, v20, 7 bitop3:0x78
	v_lshlrev_b32_e32 v137, 4, v20
	v_bitop3_b32 v20, v56, v21, 4 bitop3:0x36
	v_lshl_add_u64 v[142:143], s[28:29], 0, v[52:53]
	v_lshlrev_b32_e32 v145, 4, v20
	v_lshlrev_b32_e32 v146, 4, v59
	v_lshlrev_b32_e32 v147, 4, v60
	v_lshlrev_b32_e32 v148, 4, v61
	v_lshlrev_b32_e32 v149, 4, v62
	v_lshl_add_u32 v150, v55, 7, 16
	v_lshl_add_u32 v151, v58, 8, 16
	v_mov_b64_e32 v[58:59], v[26:27]
	v_mov_b64_e32 v[66:67], v[26:27]
	v_mov_b64_e32 v[70:71], v[26:27]
	v_mov_b64_e32 v[20:21], v[76:77]
	v_mov_b64_e32 v[36:37], v[76:77]
	v_mov_b64_e32 v[40:41], v[76:77]
	v_mov_b64_e32 v[48:49], v[76:77]
	v_mov_b64_e32 v[52:53], v[76:77]
	v_mov_b64_e32 v[60:61], v[76:77]
	v_mov_b64_e32 v[72:73], v[76:77]
	v_mov_b64_e32 v[46:47], v[26:27]
	v_mov_b64_e32 v[34:35], v[26:27]
	v_mov_b64_e32 v[30:31], v[26:27]
	v_mov_b64_e32 v[82:83], v[26:27]
	v_cndmask_b32_e64 v2, v2, 33, s[26:27]
	s_mov_b32 s11, 0
	s_xor_b64 s[26:27], s[12:13], -1
	s_mov_b32 s34, 0
	v_mov_b64_e32 v[56:57], v[24:25]
	v_mov_b64_e32 v[64:65], v[24:25]
	v_mov_b64_e32 v[68:69], v[24:25]
	v_mov_b64_e32 v[22:23], v[78:79]
	v_mov_b64_e32 v[38:39], v[78:79]
	v_mov_b64_e32 v[42:43], v[78:79]
	v_mov_b64_e32 v[50:51], v[78:79]
	v_mov_b64_e32 v[54:55], v[78:79]
	v_mov_b64_e32 v[62:63], v[78:79]
	v_mov_b64_e32 v[74:75], v[78:79]
	v_mov_b64_e32 v[44:45], v[24:25]
	v_mov_b64_e32 v[32:33], v[24:25]
	v_mov_b64_e32 v[28:29], v[24:25]
	v_mov_b64_e32 v[80:81], v[24:25]
	s_mov_b32 s30, 0
	s_branch .LBB0_1370

; #define MFMA16(a, b, c) __builtin_amdgcn_mfma_f32_16x16x32_bf16((a), (b), (c), 0, 0, 0)
; DI int kswz(int key) { return (((key >> 3) & 3) << 2) | (key & 3); }
; DI void attn_item(const Params& p, int l, bool isS, int b, int h, int cp, char* smem) {
;     ...
;   auto issue_k = [&](int kt) {
; #pragma unroll
;     for (int i = 0; i < 2; ++i)
;       __builtin_amdgcn_global_load_lds((const unsigned*)(Kg + (size_t)(kt * 64 + kkey + i * 32) * 512 + kgch * 8), (unsigned*)(Ks + (kt & 1) * 16384 + soff + i * 8192), 16, 0, 0);
;   };
;   auto issue_v = [&](int kt) {
; #pragma unroll
;     for (int i = 0; i < 2; ++i)
;       __builtin_amdgcn_global_load_lds((const unsigned*)(Vg + (size_t)(vvd + i * 64) * vstride + kt * 64 + vgch * 8), (unsigned*)(Vs + (kt & 1) * 16384 + soff + i * 8192), 16, 0, 0);
;   };
;   auto qk_tile = [&](int kt, f32x4 (&st)[2][4]) {
;     const char* Kb = Ks + (kt & 1) * 16384;
;     bf16x8 kf[2][4][2];
; #pragma unroll
;     for (int mp = 0; mp < 2; ++mp)
; #pragma unroll
;       for (int mt = 0; mt < 4; ++mt) {
;         const int key = 32 * (mt >> 1) + 8 * (fr >> 2) + 4 * (mt & 1) + (fr & 3);
; #pragma unroll
;         for (int ks = 0; ks < 2; ++ks) kf[mp][mt][ks] = *(const bf16x8*)(Kb + key * 256 + (((mp * 8 + ks * 4 + fq) ^ kswz(key)) << 4));
;       }
; #pragma unroll
;     for (int mp = 0; mp < 2; ++mp)
; #pragma unroll
;       for (int mt = 0; mt < 4; ++mt) {
;         f32x4 a = MFMA16(kf[mp][mt][0], qf[mp][0], (f32x4{0.f, 0.f, 0.f, 0.f}));
;         st[mp][mt] = MFMA16(kf[mp][mt][1], qf[mp][1], a);
.LBB0_1369:
.LBB0_1370:
	s_add_i32 s20, s34, 0x4000
	s_and_b32 s20, s20, 0x4000
	v_add_u32_e32 v248, s20, v151
	v_add_u32_e32 v170, v248, v146
	v_add_u32_e32 v171, v248, v147
	v_add_u32_e32 v242, v248, v148
	v_add_u32_e32 v243, v248, v149
	s_and_b32 s24, s34, 0x4000
	v_add_u32_e32 v249, s24, v150
	v_add_u32_e32 v244, v249, v137
	v_add_u32_e32 v245, v249, v145
	ds_read_b128 v[154:157], v170
	ds_read_b128 v[158:161], v171
	ds_read_b128 v[162:165], v170 offset:1024
	ds_read_b128 v[166:169], v171 offset:1024
	ds_read_b128 v[176:179], v170 offset:8192
	ds_read_b128 v[180:183], v171 offset:8192
	ds_read_b128 v[198:201], v170 offset:9216
	ds_read_b128 v[202:205], v171 offset:9216
	ds_read_b128 v[206:209], v242
	ds_read_b128 v[214:217], v243
	ds_read_b128 v[218:221], v242 offset:1024
	ds_read_b128 v[222:225], v243 offset:1024
	ds_read_b128 v[226:229], v242 offset:8192
	ds_read_b128 v[230:233], v243 offset:8192
	ds_read_b128 v[234:237], v242 offset:9216
	s_waitcnt lgkmcnt(13)
	v_mfma_f32_16x16x32_bf16 v[124:127], v[154:157], v[8:11], 0
	v_mfma_f32_16x16x32_bf16 v[124:127], v[158:161], v[4:7], v[124:127]
	ds_read_b128 v[238:241], v243 offset:9216
	s_waitcnt lgkmcnt(12)
	v_mfma_f32_16x16x32_bf16 v[120:123], v[162:165], v[8:11], 0
	v_mfma_f32_16x16x32_bf16 v[120:123], v[166:169], v[4:7], v[120:123]
	s_waitcnt lgkmcnt(10)
	v_mfma_f32_16x16x32_bf16 v[112:115], v[176:179], v[8:11], 0
	v_mfma_f32_16x16x32_bf16 v[112:115], v[180:183], v[4:7], v[112:115]
	s_waitcnt lgkmcnt(8)
	v_mfma_f32_16x16x32_bf16 v[116:119], v[198:201], v[8:11], 0
	v_mfma_f32_16x16x32_bf16 v[116:119], v[202:205], v[4:7], v[116:119]
	s_add_i32 s20, s30, 2
	s_cmp_ge_i32 s20, s9
	s_cbranch_scc1 .Lat_nokdma
	v_add_u32_e32 v102, s11, v136
	s_and_b32 s20, s34, 0x4000
	v_add_u32_e32 v100, 0x80, v102
	v_ashrrev_i32_e32 v101, 31, v100
	v_add_u32_e32 v103, s20, v133
	v_lshlrev_b64 v[100:101], 10, v[100:101]
	v_readfirstlane_b32 s20, v103
	v_lshl_add_u64 v[100:101], v[142:143], 0, v[100:101]
	s_mov_b32 m0, s20
	s_nop 0
	global_load_lds_dwordx4 v[100:101], off
	v_add_u32_e32 v100, 0xa0, v102
	v_ashrrev_i32_e32 v101, 31, v100
	v_add_u32_e32 v102, 0x2000, v103
	v_lshlrev_b64 v[100:101], 10, v[100:101]
	v_readfirstlane_b32 s20, v102
	v_lshl_add_u64 v[100:101], v[142:143], 0, v[100:101]
	s_mov_b32 m0, s20
	s_nop 0
	global_load_lds_dwordx4 v[100:101], off
